# P0: silu(c) staging straight-lined with 12 loads in flight
# speedup vs baseline: 1.0075x; 1.0075x over previous
; #define LAS __attribute__((address_space(3)))
; __global__ void __launch_bounds__(NWAVES * 64, 2) fwd_megakernel(Params P) {
;     ...
;         __syncthreads();
;         LAS float* sc = (LAS float*)lds;
;         LAS float* part = (LAS float*)(lds + 32768);
;         for (int i = tid; i < 6 * 1024; i += 512) { const int s = i >> 10, k = i & 1023; const float c = s < 2 ? P.in[2][s * 1024 + k] : P.in[3][(s - 2) * 1024 + k]; sc[i] = c / (1.0f + __expf(-c)); }
.LBB0_37:
	s_load_dwordx16 s[36:51], s[0:1], 0x0
	s_movk_i32 s0, 0x1800
	v_cmp_gt_i32_e32 vcc, s0, v26
	v_ashrrev_i32_e32 v27, 31, v26
	s_waitcnt lgkmcnt(0)
	s_barrier
	s_and_saveexec_b64 s[0:1], vcc
	s_cbranch_execz .LBB0_42
; __global__ void __launch_bounds__(NWAVES * 64, 2) fwd_megakernel(Params P) {
;     ...
;         for (int i = tid; i < 6 * 1024; i += 512) { const int s = i >> 10, k = i & 1023; const float c = s < 2 ? P.in[2][s * 1024 + k] : P.in[3][(s - 2) * 1024 + k]; sc[i] = c / (1.0f + __expf(-c)); }
	v_mov_b32_e32 v2, s40
	v_mov_b32_e32 v3, s41
	v_lshl_add_u64 v[2:3], v[26:27], 2, v[2:3]
	v_lshl_add_u32 v1, v26, 2, 0
	s_mov_b64 s[4:5], 0
	s_movk_i32 s14, 0x7ff
	v_mov_b32_e32 v5, 0
	s_mov_b64 s[6:7], 0x800
	s_movk_i32 s15, 0x15ff
	v_lshl_add_u64 v[6:7], v[26:27], 2, s[42:43]
	global_load_dword v236, v[2:3], off
	global_load_dword v237, v[2:3], off offset:2048
	s_mov_b64 s[4:5], 0x1000
	v_lshl_add_u64 v[2:3], v[2:3], 0, s[4:5]
	global_load_dword v238, v[2:3], off
	global_load_dword v239, v[2:3], off offset:2048
	global_load_dword v240, v[6:7], off
	global_load_dword v241, v[6:7], off offset:2048
	v_lshl_add_u64 v[6:7], v[6:7], 0, s[4:5]
	global_load_dword v242, v[6:7], off
	global_load_dword v243, v[6:7], off offset:2048
	v_lshl_add_u64 v[6:7], v[6:7], 0, s[4:5]
	global_load_dword v244, v[6:7], off
	global_load_dword v245, v[6:7], off offset:2048
	v_lshl_add_u64 v[6:7], v[6:7], 0, s[4:5]
	global_load_dword v246, v[6:7], off
	global_load_dword v247, v[6:7], off offset:2048
	s_waitcnt vmcnt(11)
	v_mul_f32_e32 v6, 0xbfb8aa3b, v236
	v_exp_f32_e32 v6, v6
	s_nop 0
	v_add_f32_e32 v6, 1.0, v6
	v_div_scale_f32 v8, s[12:13], v6, v6, v236
	v_rcp_f32_e32 v9, v8
	v_div_scale_f32 v10, vcc, v236, v6, v236
	v_fma_f32 v11, -v8, v9, 1.0
	v_fmac_f32_e32 v9, v11, v9
	v_mul_f32_e32 v11, v10, v9
	v_fma_f32 v12, -v8, v11, v10
	v_fmac_f32_e32 v11, v12, v9
	v_fma_f32 v8, -v8, v11, v10
	v_div_fmas_f32 v8, v8, v9, v11
	v_div_fixup_f32 v4, v8, v6, v236
	ds_write_b32 v1, v4
	s_waitcnt vmcnt(10)
	v_mul_f32_e32 v6, 0xbfb8aa3b, v237
	v_exp_f32_e32 v6, v6
	s_nop 0
	v_add_f32_e32 v6, 1.0, v6
	v_div_scale_f32 v8, s[12:13], v6, v6, v237
	v_rcp_f32_e32 v9, v8
	v_div_scale_f32 v10, vcc, v237, v6, v237
	v_fma_f32 v11, -v8, v9, 1.0
	v_fmac_f32_e32 v9, v11, v9
	v_mul_f32_e32 v11, v10, v9
	v_fma_f32 v12, -v8, v11, v10
	v_fmac_f32_e32 v11, v12, v9
	v_fma_f32 v8, -v8, v11, v10
	v_div_fmas_f32 v8, v8, v9, v11
	v_div_fixup_f32 v4, v8, v6, v237
	ds_write_b32 v1, v4 offset:2048
	s_waitcnt vmcnt(9)
	v_mul_f32_e32 v6, 0xbfb8aa3b, v238
	v_exp_f32_e32 v6, v6
	s_nop 0
	v_add_f32_e32 v6, 1.0, v6
	v_div_scale_f32 v8, s[12:13], v6, v6, v238
	v_rcp_f32_e32 v9, v8
	v_div_scale_f32 v10, vcc, v238, v6, v238
	v_fma_f32 v11, -v8, v9, 1.0
	v_fmac_f32_e32 v9, v11, v9
	v_mul_f32_e32 v11, v10, v9
	v_fma_f32 v12, -v8, v11, v10
	v_fmac_f32_e32 v11, v12, v9
	v_fma_f32 v8, -v8, v11, v10
	v_div_fmas_f32 v8, v8, v9, v11
	v_div_fixup_f32 v4, v8, v6, v238
	ds_write_b32 v1, v4 offset:4096
	s_waitcnt vmcnt(8)
	v_mul_f32_e32 v6, 0xbfb8aa3b, v239
	v_exp_f32_e32 v6, v6
	s_nop 0
	v_add_f32_e32 v6, 1.0, v6
	v_div_scale_f32 v8, s[12:13], v6, v6, v239
	v_rcp_f32_e32 v9, v8
	v_div_scale_f32 v10, vcc, v239, v6, v239
	v_fma_f32 v11, -v8, v9, 1.0
	v_fmac_f32_e32 v9, v11, v9
	v_mul_f32_e32 v11, v10, v9
	v_fma_f32 v12, -v8, v11, v10
	v_fmac_f32_e32 v11, v12, v9
	v_fma_f32 v8, -v8, v11, v10
	v_div_fmas_f32 v8, v8, v9, v11
	v_div_fixup_f32 v4, v8, v6, v239
	ds_write_b32 v1, v4 offset:6144
	s_waitcnt vmcnt(7)
	v_mul_f32_e32 v6, 0xbfb8aa3b, v240
	v_exp_f32_e32 v6, v6
	s_nop 0
	v_add_f32_e32 v6, 1.0, v6
	v_div_scale_f32 v8, s[12:13], v6, v6, v240
	v_rcp_f32_e32 v9, v8
	v_div_scale_f32 v10, vcc, v240, v6, v240
	v_fma_f32 v11, -v8, v9, 1.0
	v_fmac_f32_e32 v9, v11, v9
	v_mul_f32_e32 v11, v10, v9
	v_fma_f32 v12, -v8, v11, v10
	v_fmac_f32_e32 v11, v12, v9
	v_fma_f32 v8, -v8, v11, v10
	v_div_fmas_f32 v8, v8, v9, v11
	v_div_fixup_f32 v4, v8, v6, v240
	ds_write_b32 v1, v4 offset:8192
	s_waitcnt vmcnt(6)
	v_mul_f32_e32 v6, 0xbfb8aa3b, v241
	v_exp_f32_e32 v6, v6
	s_nop 0
	v_add_f32_e32 v6, 1.0, v6
	v_div_scale_f32 v8, s[12:13], v6, v6, v241
	v_rcp_f32_e32 v9, v8
	v_div_scale_f32 v10, vcc, v241, v6, v241
	v_fma_f32 v11, -v8, v9, 1.0
	v_fmac_f32_e32 v9, v11, v9
	v_mul_f32_e32 v11, v10, v9
	v_fma_f32 v12, -v8, v11, v10
	v_fmac_f32_e32 v11, v12, v9
	v_fma_f32 v8, -v8, v11, v10
	v_div_fmas_f32 v8, v8, v9, v11
	v_div_fixup_f32 v4, v8, v6, v241
	ds_write_b32 v1, v4 offset:10240
	s_waitcnt vmcnt(5)
	v_mul_f32_e32 v6, 0xbfb8aa3b, v242
	v_exp_f32_e32 v6, v6
	s_nop 0
	v_add_f32_e32 v6, 1.0, v6
	v_div_scale_f32 v8, s[12:13], v6, v6, v242
	v_rcp_f32_e32 v9, v8
	v_div_scale_f32 v10, vcc, v242, v6, v242
	v_fma_f32 v11, -v8, v9, 1.0
	v_fmac_f32_e32 v9, v11, v9
	v_mul_f32_e32 v11, v10, v9
	v_fma_f32 v12, -v8, v11, v10
	v_fmac_f32_e32 v11, v12, v9
	v_fma_f32 v8, -v8, v11, v10
	v_div_fmas_f32 v8, v8, v9, v11
	v_div_fixup_f32 v4, v8, v6, v242
	ds_write_b32 v1, v4 offset:12288
	s_waitcnt vmcnt(4)
	v_mul_f32_e32 v6, 0xbfb8aa3b, v243
	v_exp_f32_e32 v6, v6
	s_nop 0
	v_add_f32_e32 v6, 1.0, v6
	v_div_scale_f32 v8, s[12:13], v6, v6, v243
	v_rcp_f32_e32 v9, v8
	v_div_scale_f32 v10, vcc, v243, v6, v243
	v_fma_f32 v11, -v8, v9, 1.0
	v_fmac_f32_e32 v9, v11, v9
	v_mul_f32_e32 v11, v10, v9
	v_fma_f32 v12, -v8, v11, v10
	v_fmac_f32_e32 v11, v12, v9
	v_fma_f32 v8, -v8, v11, v10
	v_div_fmas_f32 v8, v8, v9, v11
	v_div_fixup_f32 v4, v8, v6, v243
	ds_write_b32 v1, v4 offset:14336
	s_waitcnt vmcnt(3)
	v_mul_f32_e32 v6, 0xbfb8aa3b, v244
	v_exp_f32_e32 v6, v6
	s_nop 0
	v_add_f32_e32 v6, 1.0, v6
	v_div_scale_f32 v8, s[12:13], v6, v6, v244
	v_rcp_f32_e32 v9, v8
	v_div_scale_f32 v10, vcc, v244, v6, v244
	v_fma_f32 v11, -v8, v9, 1.0
	v_fmac_f32_e32 v9, v11, v9
	v_mul_f32_e32 v11, v10, v9
	v_fma_f32 v12, -v8, v11, v10
	v_fmac_f32_e32 v11, v12, v9
	v_fma_f32 v8, -v8, v11, v10
	v_div_fmas_f32 v8, v8, v9, v11
	v_div_fixup_f32 v4, v8, v6, v244
	ds_write_b32 v1, v4 offset:16384
	s_waitcnt vmcnt(2)
	v_mul_f32_e32 v6, 0xbfb8aa3b, v245
	v_exp_f32_e32 v6, v6
	s_nop 0
	v_add_f32_e32 v6, 1.0, v6
	v_div_scale_f32 v8, s[12:13], v6, v6, v245
	v_rcp_f32_e32 v9, v8
	v_div_scale_f32 v10, vcc, v245, v6, v245
	v_fma_f32 v11, -v8, v9, 1.0
	v_fmac_f32_e32 v9, v11, v9
	v_mul_f32_e32 v11, v10, v9
	v_fma_f32 v12, -v8, v11, v10
	v_fmac_f32_e32 v11, v12, v9
	v_fma_f32 v8, -v8, v11, v10
	v_div_fmas_f32 v8, v8, v9, v11
	v_div_fixup_f32 v4, v8, v6, v245
	ds_write_b32 v1, v4 offset:18432
	s_waitcnt vmcnt(1)
	v_mul_f32_e32 v6, 0xbfb8aa3b, v246
	v_exp_f32_e32 v6, v6
	s_nop 0
	v_add_f32_e32 v6, 1.0, v6
	v_div_scale_f32 v8, s[12:13], v6, v6, v246
	v_rcp_f32_e32 v9, v8
	v_div_scale_f32 v10, vcc, v246, v6, v246
	v_fma_f32 v11, -v8, v9, 1.0
	v_fmac_f32_e32 v9, v11, v9
	v_mul_f32_e32 v11, v10, v9
	v_fma_f32 v12, -v8, v11, v10
	v_fmac_f32_e32 v11, v12, v9
	v_fma_f32 v8, -v8, v11, v10
	v_div_fmas_f32 v8, v8, v9, v11
	v_div_fixup_f32 v4, v8, v6, v246
	ds_write_b32 v1, v4 offset:20480
	s_waitcnt vmcnt(0)
	v_mul_f32_e32 v6, 0xbfb8aa3b, v247
	v_exp_f32_e32 v6, v6
	s_nop 0
	v_add_f32_e32 v6, 1.0, v6
	v_div_scale_f32 v8, s[12:13], v6, v6, v247
	v_rcp_f32_e32 v9, v8
	v_div_scale_f32 v10, vcc, v247, v6, v247
	v_fma_f32 v11, -v8, v9, 1.0
	v_fmac_f32_e32 v9, v11, v9
	v_mul_f32_e32 v11, v10, v9
	v_fma_f32 v12, -v8, v11, v10
	v_fmac_f32_e32 v11, v12, v9
	v_fma_f32 v8, -v8, v11, v10
	v_div_fmas_f32 v8, v8, v9, v11
	v_div_fixup_f32 v4, v8, v6, v247
	ds_write_b32 v1, v4 offset:22528
